# prep pass 3: base pointers kept in v255 lanes and read with v_readlane instead of 11 s_load_dwordx2 + lgkmcnt(0) per loop iteration
# baseline (speedup 1.0000x reference)
.LBB0_1172:
	s_or_b64 exec, exec, s[22:23]
	s_and_saveexec_b64 s[22:23], vcc
	s_cbranch_execz .LBB0_1226
	v_readlane_b32 s4, v254, 29
	v_readlane_b32 s5, v254, 30
	s_lshl_b64 s[2:3], s[4:5], 9
	s_add_u32 s2, s24, s2
	s_addc_u32 s3, s25, s3
	v_lshlrev_b32_e32 v14, 3, v71
	global_load_dwordx2 v[18:19], v14, s[2:3]
	s_lshl_b64 s[2:3], s[4:5], 10
	s_add_u32 s2, s6, s2
	s_addc_u32 s3, s7, s3
	s_lshl_b64 s[4:5], s[4:5], 8
	s_waitcnt lgkmcnt(0)
	s_add_u32 s6, s8, s4
	s_addc_u32 s7, s9, s5
	s_add_u32 s4, s10, s4
	v_lshlrev_b32_e32 v0, 4, v92
	s_addc_u32 s5, s11, s5
	v_and_b32_e32 v0, 0xf0, v0
	global_load_dwordx4 v[2:5], v0, s[4:5]
	global_load_dwordx4 v[6:9], v0, s[6:7]
	global_load_dwordx4 v[10:13], v80, s[2:3]
	v_readlane_b32 s2, v254, 25
	v_readlane_b32 s3, v254, 26
	v_and_b32_e32 v20, 0x70, v74
	s_load_dwordx2 s[98:99], s[2:3], 0x110
	s_load_dwordx2 s[2:3], s[2:3], 0x118
	v_lshlrev_b32_e32 v0, 1, v20
	v_lshl_add_u64 v[22:23], s[16:17], 0, v[0:1]
	v_and_b32_e32 v0, 4, v92
	v_cmp_eq_u32_e64 s[10:11], 0, v0
	v_and_b32_e32 v0, 8, v92
	v_cmp_lt_i32_e32 vcc, v207, v206
	v_cmp_eq_u32_e64 s[12:13], 0, v0
	s_waitcnt lgkmcnt(0)
	v_writelane_b32 v255, s2, 52
	v_writelane_b32 v255, s3, 53
	v_writelane_b32 v255, s98, 54
	v_writelane_b32 v255, s99, 55
	s_add_u32 s24, s2, 0x5000
	v_cndmask_b32_e32 v0, v204, v207, vcc
	v_cmp_lt_i32_e32 vcc, v208, v206
	v_lshlrev_b32_e32 v68, 2, v0
	s_addc_u32 s25, s3, 0
	v_cndmask_b32_e32 v0, v204, v208, vcc
	v_cmp_lt_i32_e32 vcc, v209, v206
	v_lshlrev_b32_e32 v69, 2, v0
	s_add_u32 s26, s2, 0x6000
	v_cndmask_b32_e32 v0, v204, v209, vcc
	v_cmp_lt_i32_e32 vcc, v220, v206
	v_lshlrev_b32_e32 v75, 2, v0
	v_mov_b32_e32 v79, v1
	v_cndmask_b32_e32 v0, v204, v220, vcc
	v_cmp_lt_i32_e32 vcc, v217, v206
	v_lshlrev_b32_e32 v77, 2, v0
	v_mov_b32_e32 v15, v1
	v_cndmask_b32_e32 v0, v204, v217, vcc
	v_cmp_lt_i32_e32 vcc, v212, v206
	s_addc_u32 s27, s3, 0
	v_lshlrev_b32_e32 v98, 3, v163
	global_load_dwordx2 v[100:101], v98, s[24:25]
	global_load_dwordx2 v[102:103], v98, s[26:27]
	v_add_u32_e32 v99, 0x1000, v98
	global_load_dwordx2 v[104:105], v99, s[26:27]
	s_waitcnt vmcnt(0)
	ds_write_b64 v98, v[100:101]
	ds_write_b64 v98, v[102:103] offset:4096
	ds_write_b64 v98, v[104:105] offset:8192
	s_waitcnt lgkmcnt(0)
	s_barrier
	v_lshlrev_b32_e32 v17, 2, v92
	v_cmp_gt_u32_e64 s[4:5], 16, v71
	v_cmp_gt_u32_e64 s[28:29], 32, v71
	v_cmp_lt_u32_e64 s[6:7], 31, v71
	v_cmp_gt_u32_e64 s[8:9], 8, v71
	v_lshl_add_u64 v[22:23], v[22:23], 0, v[78:79]
	v_lshlrev_b32_e32 v79, 2, v0
	v_cndmask_b32_e32 v0, v204, v212, vcc
	v_lshl_add_u64 v[14:15], s[2:3], 0, v[14:15]
	s_mov_b64 s[2:3], 0xb134000
	v_ashrrev_i32_e32 v71, 31, v70
	v_lshlrev_b32_e32 v80, 2, v0
	v_lshl_add_u64 v[24:25], v[14:15], 0, s[2:3]
	v_lshlrev_b64 v[14:15], 6, v[70:71]
	v_and_b32_e32 v0, 0xe0, v17
	v_lshl_add_u64 v[14:15], v[14:15], 0, v[0:1]
	v_or_b32_e32 v14, v14, v78
	s_mov_b64 s[2:3], 0xcbb4000
	s_movk_i32 s1, 0x300
	v_lshl_add_u64 v[26:27], v[14:15], 0, s[2:3]
	v_mad_i64_i32 v[14:15], s[2:3], v70, s1, 0
	v_lshlrev_b32_e32 v0, 3, v92
	v_or_b32_e32 v14, v14, v72
	s_mov_b64 s[2:3], 0x2134200
	v_and_b32_e32 v0, 0x1f8, v0
	v_lshl_add_u64 v[28:29], v[14:15], 0, s[2:3]
	v_mad_i64_i32 v[14:15], s[2:3], v70, s1, v[0:1]
	v_mov_b32_e32 v73, v1
	s_mov_b64 s[2:3], 0x2134000
	s_movk_i32 s1, 0x740
	v_lshl_add_u64 v[30:31], v[14:15], 0, s[2:3]
	v_mad_i64_i32 v[34:35], s[2:3], v70, s1, 0
	v_mad_i64_i32 v[14:15], s[2:3], v70, s1, v[72:73]
	s_mov_b64 s[2:3], 0x5134200
	s_lshl_b32 s30, s0, 4
	s_mul_i32 s36, s0, 0x3000
	v_lshl_add_u64 v[36:37], v[14:15], 0, s[2:3]
	s_mul_i32 s40, s0, 0x7400
	v_mad_i64_i32 v[14:15], s[0:1], v70, s1, v[0:1]
	v_and_or_b32 v16, v74, 16, v76
	s_ashr_i32 s31, s30, 31
	v_lshlrev_b64 v[32:33], 10, v[70:71]
	s_mov_b64 s[0:1], 0x5134000
	v_and_b32_e32 v21, 12, v17
	s_lshl_b64 s[34:35], s[30:31], 6
	s_mul_hi_i32 s37, s30, 0x300
	v_or_b32_e32 v32, v32, v0
	s_lshl_b64 s[38:39], s[30:31], 10
	s_mul_hi_i32 s41, s30, 0x740
	v_lshl_or_b32 v34, v16, 1, v34
	v_lshl_add_u64 v[38:39], v[14:15], 0, s[0:1]
	s_mov_b64 s[42:43], 0
	v_lshlrev_b32_e32 v40, 1, v16
	s_branch .LBB0_1175

.LBB0_1175:
	v_readlane_b32 s0, v254, 25
	v_readlane_b32 s1, v254, 26
	v_readlane_b32 s2, v255, 52
	v_readlane_b32 s3, v255, 53
	v_mov_b32_e32 v73, 0
	s_waitcnt lgkmcnt(0)
	v_lshl_add_u64 v[14:15], s[2:3], 0, v[38:39]
	global_load_dwordx2 v[60:61], v[14:15], off
	v_lshl_add_u64 v[14:15], s[2:3], 0, v[36:37]
	global_load_dword v62, v[14:15], off
	v_mov_b32_e32 v14, 0
	s_and_saveexec_b64 s[14:15], s[4:5]
	s_cbranch_execz .LBB0_1177
	v_lshl_add_u64 v[16:17], s[2:3], 0, v[34:35]
	v_add_co_u32_e32 v16, vcc, 0x5134000, v16
	s_nop 1
	v_addc_co_u32_e32 v17, vcc, 0, v17, vcc
	global_load_ushort v98, v[16:17], off offset:768
	global_load_ushort v99, v[16:17], off offset:784

.LBB0_1189:
	s_or_b64 exec, exec, s[46:47]
	s_mov_b64 s[0:1], 0xb134000
	s_waitcnt vmcnt(2)
	s_and_saveexec_b64 s[98:99], s[4:5]
	v_lshl_or_b32 v73, v99, 16, v98
	v_lshl_or_b32 v41, v101, 16, v100
	s_or_b64 exec, exec, s[98:99]
	v_and_b32_e32 v83, 0xffff0000, v60
	v_and_b32_e32 v65, 0xffff0000, v61
	v_and_b32_e32 v64, s0, v60
	v_lshlrev_b32_e32 v82, 16, v60
	v_mul_f32_e32 v60, v83, v83
	v_lshlrev_b32_e32 v66, 16, v61
	v_mov_b32_e32 v67, v65
	v_pk_fma_f32 v[60:61], v[82:83], v[82:83], v[60:61] op_sel_hi:[1,1,0]
	s_waitcnt vmcnt(1)
	v_lshlrev_b32_e32 v84, 16, v62
	v_and_b32_e32 v85, 0xffff0000, v62
	v_pk_mul_f32 v[64:65], v[64:65], v[64:65]
	v_pk_fma_f32 v[60:61], v[66:67], v[66:67], v[60:61]
	v_pk_mul_f32 v[62:63], v[84:85], v[84:85]
	v_cndmask_b32_e64 v53, v213, v214, s[16:17]
	v_mov_b32_e32 v64, v62
	v_pk_mov_b32 v[60:61], v[62:63], v[60:61] op_sel:[1,0]
	v_lshl_add_u64 v[16:17], v[56:57], 0, s[0:1]
	v_pk_add_f32 v[60:61], v[64:65], v[60:61]
	ds_bpermute_b32 v63, v68, v61
	ds_bpermute_b32 v62, v68, v60
	v_readlane_b32 s0, v254, 29
	v_readlane_b32 s1, v254, 30
	v_readlane_b32 s2, v254, 25
	v_readlane_b32 s3, v254, 26
	s_waitcnt lgkmcnt(0)
	v_pk_add_f32 v[60:61], v[60:61], v[62:63]
	ds_bpermute_b32 v63, v69, v61
	ds_bpermute_b32 v62, v69, v60
	v_readlane_b32 s2, v255, 52
	v_readlane_b32 s3, v255, 53
	s_waitcnt lgkmcnt(0)
	v_pk_add_f32 v[60:61], v[60:61], v[62:63]
	ds_bpermute_b32 v63, v75, v61
	ds_bpermute_b32 v62, v75, v60
	s_waitcnt lgkmcnt(0)
	v_pk_add_f32 v[60:61], v[60:61], v[62:63]
	ds_bpermute_b32 v63, v77, v61
	ds_bpermute_b32 v62, v77, v60
	s_waitcnt lgkmcnt(0)
	v_pk_add_f32 v[60:61], v[60:61], v[62:63]
	ds_bpermute_b32 v65, v79, v61
	ds_bpermute_b32 v64, v79, v60
	v_ashrrev_i32_e32 v63, 7, v70
	v_and_b32_e32 v62, v53, v70
	v_and_b32_e32 v53, -2, v63
	v_cndmask_b32_e64 v53, 0, v53, s[16:17]
	s_waitcnt lgkmcnt(0)
	v_pk_add_f32 v[60:61], v[60:61], v[64:65]
	ds_bpermute_b32 v65, v80, v61
	ds_bpermute_b32 v64, v80, v60
	v_add_u32_e32 v86, s0, v53
	s_brev_b32 s0, 60
	s_mov_b32 s1, 0x3b800000
	v_ashrrev_i32_e32 v87, 31, v86
	s_waitcnt lgkmcnt(0)
	v_pk_add_f32 v[60:61], v[60:61], v[64:65]
	v_lshlrev_b64 v[86:87], 8, v[86:87]
	v_pk_fma_f32 v[60:61], v[60:61], s[0:1], v[162:163] op_sel_hi:[1,1,0]
	s_mov_b32 s0, 0x800000
	v_mul_f32_e32 v53, 0x4b800000, v61
	v_cmp_gt_f32_e32 vcc, s0, v61
	v_mov_b32_e32 v63, v1
	v_lshl_add_u64 v[64:65], v[86:87], 0, v[62:63]
	v_cndmask_b32_e32 v53, v61, v53, vcc
	v_rsq_f32_e32 v53, v53
	v_lshl_add_u64 v[86:87], s[2:3], 0, v[30:31]
	v_mul_f32_e32 v61, 0x45800000, v53
	v_cndmask_b32_e32 v78, v53, v61, vcc
	v_mul_f32_e32 v53, 0x4b800000, v60
	v_cmp_gt_f32_e32 vcc, s0, v60
	v_pk_mul_f32 v[82:83], v[78:79], v[82:83] op_sel_hi:[0,1]
	v_pk_mul_f32 v[66:67], v[78:79], v[66:67] op_sel_hi:[0,1]
	v_cndmask_b32_e32 v53, v60, v53, vcc
	v_rsq_f32_e32 v53, v53
	v_pk_mul_f32 v[82:83], v[10:11], v[82:83]
	v_pk_mul_f32 v[66:67], v[12:13], v[66:67]
	v_cvt_pk_bf16_f32 v60, v82, v83
	v_cvt_pk_bf16_f32 v61, v66, v67
	s_waitcnt vmcnt(0)
	global_store_dwordx2 v[86:87], v[60:61], off
	v_mul_f32_e32 v60, 0x45800000, v53
	v_cndmask_b32_e32 v60, v53, v60, vcc
	v_pk_mul_f32 v[60:61], v[60:61], v[84:85] op_sel_hi:[0,1]
	v_pk_mul_f32 v[66:67], v[18:19], v[60:61]
	v_lshl_add_u64 v[60:61], s[2:3], 0, v[28:29]
	v_cvt_pk_bf16_f32 v53, v66, v67
	global_store_dword v[60:61], v53, off
	v_lshlrev_b64 v[60:61], 9, v[64:65]
	s_and_saveexec_b64 s[46:47], s[16:17]
	s_cbranch_execz .LBB0_1191
	v_readlane_b32 s0, v254, 25
	v_readlane_b32 s1, v254, 26
	v_readlane_b32 s0, v255, 54
	v_readlane_b32 s1, v255, 55
	v_lshlrev_b32_e32 v82, 2, v74
	v_mov_b32_e32 v83, v1
	s_waitcnt lgkmcnt(0)
	v_lshl_add_u64 v[84:85], s[0:1], 0, v[60:61]
	v_lshl_add_u64 v[82:83], v[84:85], 0, v[82:83]
	v_add_co_u32_e32 v82, vcc, 0x6000000, v82
	s_nop 1
	v_addc_co_u32_e32 v83, vcc, 0, v83, vcc
	global_store_dwordx2 v[82:83], v[66:67], off

.LBB0_1194:
	s_andn2_saveexec_b64 s[46:47], s[46:47]
	s_cbranch_execz .LBB0_1196
	v_readlane_b32 s0, v254, 25
	v_readlane_b32 s1, v254, 26
	v_readlane_b32 s0, v255, 54
	v_readlane_b32 s1, v255, 55
	v_lshlrev_b64 v[64:65], 7, v[64:65]
	v_lshlrev_b32_e32 v82, 2, v20
	v_mov_b32_e32 v83, v1
	s_waitcnt lgkmcnt(0)
	v_lshl_add_u64 v[64:65], s[0:1], 0, v[64:65]
	v_lshl_add_u64 v[64:65], v[64:65], 0, v[82:83]
	v_lshlrev_b32_e32 v82, 2, v76
	v_lshl_add_u64 v[64:65], v[64:65], 0, v[82:83]
	s_mov_b64 s[0:1], 0x6800000
	v_lshl_add_u64 v[82:83], v[64:65], 0, s[0:1]
	v_add_co_u32_e32 v64, vcc, 0x6800000, v64
	s_nop 1
	v_addc_co_u32_e32 v65, vcc, 0, v65, vcc
	global_store_dword v[64:65], v66, off
	global_store_dword v[82:83], v67, off offset:32
.LBB0_1196:
	s_or_b64 exec, exec, s[46:47]
	v_readlane_b32 s0, v254, 25
	v_readlane_b32 s1, v254, 26
	v_readlane_b32 s0, v255, 52
	v_readlane_b32 s1, v255, 53
	v_cvt_pk_bf16_f32 v53, v66, v67
	s_waitcnt lgkmcnt(0)
	v_lshl_add_u64 v[64:65], s[0:1], 0, v[26:27]
	global_store_dword v[64:65], v53, off

.LBB0_1204:
	v_readlane_b32 s0, v254, 25
	v_readlane_b32 s1, v254, 26
	v_readlane_b32 s0, v255, 54
	v_readlane_b32 s1, v255, 55
	v_mov_b32_e32 v55, v1
	s_waitcnt lgkmcnt(0)
	v_lshl_add_u64 v[62:63], s[0:1], 0, v[60:61]
	v_lshl_add_u64 v[62:63], v[62:63], 0, v[54:55]
	v_add_co_u32_e32 v62, vcc, 0x6a00000, v62
	s_nop 1
	v_addc_co_u32_e32 v63, vcc, 0, v63, vcc
	global_store_dwordx4 v[62:63], v[14:17], off
	s_or_b64 exec, exec, s[16:17]
	s_and_saveexec_b64 s[16:17], s[14:15]
	s_cbranch_execz .LBB0_1201

.LBB0_1207:
	v_readlane_b32 s0, v254, 25
	v_readlane_b32 s1, v254, 26
	v_readlane_b32 s0, v255, 54
	v_readlane_b32 s1, v255, 55
	v_mov_b32_e32 v55, v1
	v_lshlrev_b32_e32 v14, 16, v58
	v_and_b32_e32 v15, 0xffff0000, v58
	v_lshlrev_b32_e32 v16, 16, v59
	s_waitcnt lgkmcnt(0)
	v_lshl_add_u64 v[56:57], s[0:1], 0, v[60:61]
	v_lshl_add_u64 v[56:57], v[56:57], 0, v[54:55]
	v_add_co_u32_e32 v56, vcc, 0x71ff000, v56
	v_and_b32_e32 v17, 0xffff0000, v59
	s_nop 0
	v_addc_co_u32_e32 v57, vcc, 0, v57, vcc
	global_store_dwordx4 v[56:57], v[14:17], off offset:3584
	s_or_b64 exec, exec, s[14:15]
	v_cmp_gt_i32_e32 vcc, s33, v50
	s_and_saveexec_b64 s[44:45], vcc
	s_cbranch_execz .LBB0_1174
.LBB0_1208:
	v_and_b32_e32 v15, 0xffff0000, v43
	v_and_b32_e32 v14, s0, v42
	v_mov_b32_e32 v57, v15
	v_pk_mul_f32 v[14:15], v[14:15], v[14:15]
	v_and_b32_e32 v59, 0xffff0000, v42
	v_lshlrev_b32_e32 v58, 16, v42
	v_mul_f32_e32 v14, v59, v59
	v_lshlrev_b32_e32 v56, 16, v43
	v_pk_fma_f32 v[16:17], v[58:59], v[58:59], v[14:15] op_sel_hi:[1,1,0]
	v_lshlrev_b32_e32 v60, 16, v71
	v_and_b32_e32 v61, 0xffff0000, v71
	v_pk_fma_f32 v[16:17], v[56:57], v[56:57], v[16:17]
	v_pk_mul_f32 v[62:63], v[60:61], v[60:61]
	s_movk_i32 s0, 0x1fff
	v_mov_b32_e32 v14, v62
	v_pk_mov_b32 v[16:17], v[62:63], v[16:17] op_sel:[1,0]
	v_cmp_lt_i32_e64 s[16:17], s0, v50
	v_pk_add_f32 v[14:15], v[14:15], v[16:17]
	ds_bpermute_b32 v17, v68, v15
	ds_bpermute_b32 v16, v68, v14
	s_movk_i32 s0, 0x2000
	v_cmp_gt_i32_e64 s[14:15], s0, v50
	v_readlane_b32 s0, v254, 29
	v_readlane_b32 s1, v254, 30
	s_waitcnt lgkmcnt(0)
	v_pk_add_f32 v[14:15], v[14:15], v[16:17]
	ds_bpermute_b32 v17, v69, v15
	ds_bpermute_b32 v16, v69, v14
	s_mov_b32 s2, 0x800000
	v_mov_b32_e32 v53, v1
	s_waitcnt lgkmcnt(0)
	v_pk_add_f32 v[14:15], v[14:15], v[16:17]
	ds_bpermute_b32 v17, v75, v15
	ds_bpermute_b32 v16, v75, v14
	s_waitcnt lgkmcnt(0)
	v_pk_add_f32 v[16:17], v[14:15], v[16:17]
	ds_bpermute_b32 v63, v77, v17
	ds_bpermute_b32 v62, v77, v16
	v_ashrrev_i32_e32 v15, 7, v50
	v_and_b32_e32 v15, -2, v15
	v_cndmask_b32_e64 v15, 0, v15, s[14:15]
	v_add_u32_e32 v64, s0, v15
	s_waitcnt lgkmcnt(0)
	v_pk_add_f32 v[16:17], v[16:17], v[62:63]
	ds_bpermute_b32 v63, v79, v17
	ds_bpermute_b32 v62, v79, v16
	v_readlane_b32 s0, v254, 33
	v_ashrrev_i32_e32 v65, 31, v64
	v_readlane_b32 s1, v254, 34
	v_cndmask_b32_e64 v14, v213, v214, s[14:15]
	s_waitcnt lgkmcnt(0)
	v_pk_add_f32 v[62:63], v[16:17], v[62:63]
	ds_bpermute_b32 v67, v80, v63
	ds_bpermute_b32 v66, v80, v62
	v_lshlrev_b64 v[16:17], 8, v[64:65]
	v_mov_b64_e32 v[64:65], s[0:1]
	s_brev_b32 s0, 60
	s_mov_b32 s1, 0x3b800000
	s_waitcnt lgkmcnt(0)
	v_pk_add_f32 v[62:63], v[62:63], v[66:67]
	v_and_b32_e32 v14, v14, v50
	v_mov_b32_e32 v15, v1
	v_pk_fma_f32 v[62:63], v[62:63], s[0:1], v[162:163] op_sel_hi:[1,1,0]
	v_lshl_add_u64 v[16:17], v[16:17], 0, v[14:15]
	v_mul_f32_e32 v15, 0x4b800000, v63
	v_cmp_gt_f32_e32 vcc, s2, v63
	s_movk_i32 s0, 0x300
	v_mad_i64_i32 v[64:65], s[0:1], v50, s0, v[64:65]
	v_cndmask_b32_e32 v15, v63, v15, vcc
	v_rsq_f32_e32 v15, v15
	v_lshl_add_u64 v[66:67], v[64:65], 0, v[0:1]
	v_lshl_add_u64 v[52:53], v[64:65], 0, v[52:53]
	v_mul_f32_e32 v0, 0x45800000, v15
	v_cndmask_b32_e32 v0, v15, v0, vcc
	v_pk_mul_f32 v[58:59], v[0:1], v[58:59] op_sel_hi:[0,1]
	v_pk_mul_f32 v[56:57], v[0:1], v[56:57] op_sel_hi:[0,1]
	v_mul_f32_e32 v0, 0x4b800000, v62
	v_cmp_gt_f32_e32 vcc, s2, v62
	v_pk_mul_f32 v[58:59], v[10:11], v[58:59]
	v_pk_mul_f32 v[56:57], v[12:13], v[56:57]
	v_cndmask_b32_e32 v0, v62, v0, vcc
	v_rsq_f32_e32 v0, v0
	v_cvt_pk_bf16_f32 v58, v58, v59
	v_cvt_pk_bf16_f32 v59, v56, v57
	global_store_dwordx2 v[66:67], v[58:59], off
	v_mul_f32_e32 v15, 0x45800000, v0
	v_cndmask_b32_e32 v0, v0, v15, vcc
	v_pk_mul_f32 v[56:57], v[0:1], v[60:61] op_sel_hi:[0,1]
	v_pk_mul_f32 v[56:57], v[18:19], v[56:57]
	s_nop 0
	v_cvt_pk_bf16_f32 v0, v56, v57
	global_store_dword v[52:53], v0, off offset:512
	v_lshlrev_b64 v[52:53], 9, v[16:17]
	s_and_saveexec_b64 s[46:47], s[14:15]
	s_cbranch_execz .LBB0_1210
	v_readlane_b32 s0, v254, 25
	v_readlane_b32 s1, v254, 26
	v_readlane_b32 s0, v255, 54
	v_readlane_b32 s1, v255, 55
	v_lshlrev_b32_e32 v0, 2, v74
	s_waitcnt lgkmcnt(0)
	v_lshl_add_u64 v[58:59], s[0:1], 0, v[52:53]
	v_lshl_add_u64 v[58:59], v[58:59], 0, v[0:1]
	v_add_co_u32_e32 v58, vcc, 0x6000000, v58
	s_nop 1
	v_addc_co_u32_e32 v59, vcc, 0, v59, vcc
	global_store_dwordx2 v[58:59], v[56:57], off

.LBB0_1213:
	s_andn2_saveexec_b64 s[48:49], s[48:49]
	s_cbranch_execz .LBB0_1215
	v_readlane_b32 s0, v254, 25
	v_readlane_b32 s1, v254, 26
	v_readlane_b32 s0, v255, 54
	v_readlane_b32 s1, v255, 55
	v_lshlrev_b64 v[16:17], 7, v[16:17]
	v_lshlrev_b32_e32 v0, 2, v20
	s_waitcnt lgkmcnt(0)
	v_lshl_add_u64 v[16:17], s[0:1], 0, v[16:17]
	v_lshl_add_u64 v[16:17], v[16:17], 0, v[0:1]
	v_lshlrev_b32_e32 v0, 2, v76
	v_lshl_add_u64 v[16:17], v[16:17], 0, v[0:1]
	s_mov_b64 s[0:1], 0x6800000
	v_lshl_add_u64 v[58:59], v[16:17], 0, s[0:1]
	v_add_co_u32_e32 v16, vcc, 0x6800000, v16
	s_nop 1
	v_addc_co_u32_e32 v17, vcc, 0, v17, vcc
	global_store_dword v[16:17], v56, off
	global_store_dword v[58:59], v57, off offset:32

.LBB0_1222:
	v_readlane_b32 s0, v254, 25
	v_readlane_b32 s1, v254, 26
	v_readlane_b32 s0, v255, 54
	v_readlane_b32 s1, v255, 55
	v_mov_b32_e32 v55, v1
	s_waitcnt lgkmcnt(0)
	v_lshl_add_u64 v[56:57], s[0:1], 0, v[52:53]
	v_lshl_add_u64 v[56:57], v[56:57], 0, v[54:55]
	v_add_co_u32_e32 v56, vcc, 0x6a00000, v56
	s_nop 1
	v_addc_co_u32_e32 v57, vcc, 0, v57, vcc
	global_store_dwordx4 v[56:57], v[14:17], off
	s_or_b64 exec, exec, s[46:47]
	s_and_saveexec_b64 s[46:47], s[16:17]
	s_cbranch_execz .LBB0_1220

.LBB0_1225:
	v_readlane_b32 s0, v254, 25
	v_readlane_b32 s1, v254, 26
	v_readlane_b32 s0, v255, 54
	v_readlane_b32 s1, v255, 55
	v_mov_b32_e32 v55, v1
	v_lshlrev_b32_e32 v14, 16, v48
	v_and_b32_e32 v15, 0xffff0000, v48
	v_lshlrev_b32_e32 v16, 16, v49
	s_waitcnt lgkmcnt(0)
	v_lshl_add_u64 v[50:51], s[0:1], 0, v[52:53]
	v_lshl_add_u64 v[50:51], v[50:51], 0, v[54:55]
	v_add_co_u32_e32 v50, vcc, 0x71ff000, v50
	v_and_b32_e32 v17, 0xffff0000, v49
	s_nop 0
	v_addc_co_u32_e32 v51, vcc, 0, v51, vcc
	global_store_dwordx4 v[50:51], v[14:17], off offset:3584
	s_branch .LBB0_1174
